# scan per-unit prefetch: P5's o|z rows are fetched only by the second half of the tickets (16 rows each) so every line is recent when P5 starts
# baseline (speedup 1.0000x reference)
.Lpf_a_go:
	s_add_u32 s26, s28, s99
	s_addc_u32 s27, s29, 0
	s_add_u32 s26, s26, s60
	s_addc_u32 s27, s27, 0
	v_mbcnt_hi_u32_b32 v46, -1, v185
	v_lshrrev_b32_e32 v45, 1, v46
	v_and_b32_e32 v47, 1, v46
	v_mul_lo_u32 v45, v45, s98
	v_mul_lo_u32 v46, v46, s98
	v_lshl_add_u32 v45, v47, 7, v45
	s_lshl_b32 s100, s98, 5
	s_add_u32 s58, s26, s61
	s_addc_u32 s59, s27, 0
	global_load_dword v44, v45, s[58:59]
	s_add_u32 s58, s58, s100
	s_addc_u32 s59, s59, 0
	global_load_dword v44, v45, s[58:59]
	s_add_u32 s58, s58, s100
	s_addc_u32 s59, s59, 0
	global_load_dword v44, v45, s[58:59]
	s_add_u32 s58, s58, s100
	s_addc_u32 s59, s59, 0
	global_load_dword v44, v45, s[58:59]
	s_add_u32 s58, s26, s73
	s_addc_u32 s59, s27, 0
	global_load_dword v44, v45, s[58:59]
	s_add_u32 s58, s58, s100
	s_addc_u32 s59, s59, 0
	global_load_dword v44, v45, s[58:59]
	s_add_u32 s58, s58, s100
	s_addc_u32 s59, s59, 0
	global_load_dword v44, v45, s[58:59]
	s_add_u32 s58, s58, s100
	s_addc_u32 s59, s59, 0
	global_load_dword v44, v45, s[58:59]
	s_add_u32 s58, s26, s72
	s_addc_u32 s59, s27, 0
	global_load_dword v44, v46, s[58:59]
	s_lshl_b32 s100, s100, 1
	s_add_u32 s58, s58, s100
	s_addc_u32 s59, s59, 0
	global_load_dword v44, v46, s[58:59]
	s_sub_u32 s58, s101, 0x200
	s_cbranch_scc1 .Lpf_a_end
	s_mul_i32 s58, s58, 0x30000
	s_add_u32 s26, s28, 0x8501000
	s_addc_u32 s27, s29, 0
	s_add_u32 s26, s26, s58
	s_addc_u32 s27, s27, 0
	v_mbcnt_hi_u32_b32 v47, -1, v185
	v_lshlrev_b32_e32 v47, 6, v47
	global_load_dword v44, v47, s[26:27]
	s_add_u32 s26, s26, 0x3000
	s_addc_u32 s27, s27, 0
	global_load_dword v44, v47, s[26:27]
	s_add_u32 s26, s26, 0x3000
	s_addc_u32 s27, s27, 0
	global_load_dword v44, v47, s[26:27]
	s_add_u32 s26, s26, 0x3000
	s_addc_u32 s27, s27, 0
	global_load_dword v44, v47, s[26:27]
	s_add_u32 s26, s26, 0x3000
	s_addc_u32 s27, s27, 0
	global_load_dword v44, v47, s[26:27]
	s_add_u32 s26, s26, 0x3000
	s_addc_u32 s27, s27, 0
	global_load_dword v44, v47, s[26:27]
	s_add_u32 s26, s26, 0x3000
	s_addc_u32 s27, s27, 0
	global_load_dword v44, v47, s[26:27]
	s_add_u32 s26, s26, 0x3000
	s_addc_u32 s27, s27, 0
	global_load_dword v44, v47, s[26:27]
	s_add_u32 s26, s26, 0x3000
	s_addc_u32 s27, s27, 0
	global_load_dword v44, v47, s[26:27]
	s_add_u32 s26, s26, 0x3000
	s_addc_u32 s27, s27, 0
	global_load_dword v44, v47, s[26:27]
	s_add_u32 s26, s26, 0x3000
	s_addc_u32 s27, s27, 0
	global_load_dword v44, v47, s[26:27]
	s_add_u32 s26, s26, 0x3000
	s_addc_u32 s27, s27, 0
	global_load_dword v44, v47, s[26:27]
	s_add_u32 s26, s26, 0x3000
	s_addc_u32 s27, s27, 0
	global_load_dword v44, v47, s[26:27]
	s_add_u32 s26, s26, 0x3000
	s_addc_u32 s27, s27, 0
	global_load_dword v44, v47, s[26:27]
	s_add_u32 s26, s26, 0x3000
	s_addc_u32 s27, s27, 0
	global_load_dword v44, v47, s[26:27]
	s_add_u32 s26, s26, 0x3000
	s_addc_u32 s27, s27, 0
	global_load_dword v44, v47, s[26:27]
